# weight conversion loops of phases 8 and 7: the two tiles of an iteration are adjacent n-tiles (512-byte contiguous source row segments)
# baseline (speedup 1.0000x reference)
; __device__ __forceinline__ void tjob_load(const TJob& j, int tile, f32x4 (&v)[4]) {
;     const int tid = threadIdx.x, nkt = j.K >> 7, tn = tile / nkt, tk = tile - tn * nkt;
;     const int n = tn * 64 + (tid & 15) * 4, kr = tid >> 4, col = map_col(j.map, n);
; #pragma unroll
;     for (int i = 0; i < 4; ++i) v[i] = col >= 0 ? __builtin_nontemporal_load((const f32x4*)(j.src + (size_t)(tk * 128 + kr + 32 * i) * j.ld_src + col)) : (f32x4){0.f, 0.f, 0.f, 0.f};
; __device__ __forceinline__ void transpose_jobs(const TJob* jobs, int njobs, int bi, int nblk, LAS unsigned char* lds) {
;     ...
;     f32x4 v[4]; int curj = 0, base = 0;
;     int t = bi;
;     auto locate = [&](int tt, int& jj, int& bb) { while (tt >= bb + (jobs[jj].Nout >> 6) * (jobs[jj].K >> 7)) { bb += (jobs[jj].Nout >> 6) * (jobs[jj].K >> 7); ++jj; } };
;     if (t < total) { locate(t, curj, base); tjob_load(jobs[curj], t - base, v); }
.LBB0_1228:
	v_and_b32_e32 v38, 60, v184
	v_mul_u32_u24_e32 v0, 0x204, v129
	s_cmpk_gt_i32 s96, 0x88
	v_lshl_add_u32 v39, v166, 2, 0
	v_mul_u32_u24_e32 v40, 0x204, v38
	v_add3_u32 v41, 0, v0, v128
	s_cbranch_scc0 .LBB0_1241
	s_mov_b64 s[8:9], 0
	s_cmpk_gt_i32 s2, 0x87
	s_mov_b64 s[6:7], 0
	s_cbranch_scc0 .LBB0_1242
	s_cmpk_lg_u32 s96, 0x100
	s_cbranch_scc1 .Ltr7_compiled
	s_waitcnt vmcnt(0)
	s_load_dwordx4 s[8:11], s[0:1], 0x150
	v_and_b32_e32 v105, 15, v160
	v_lshrrev_b32_e32 v106, 4, v160
	v_lshrrev_b32_e32 v107, 3, v160
	v_and_b32_e32 v108, 7, v160
	v_mul_u32_u24_e32 v100, 0x2000, v106
	v_lshl_add_u32 v100, v105, 4, v100
	v_mul_u32_u24_e32 v102, 2064, v105
	v_lshl_add_u32 v102, v106, 2, v102
	v_mul_u32_u24_e32 v103, 516, v107
	v_lshl_add_u32 v103, v108, 6, v103
	v_add_u32_e32 v104, 0x8400, v103
	v_mul_u32_u24_e32 v101, 0x2c00, v107
	v_lshl_add_u32 v101, v108, 5, v101
	s_sub_i32 s12, s2, 136
	s_mul_i32 s50, s12, 1490
	s_lshr_b32 s50, s50, 16
	s_mul_i32 s51, s50, 44
	s_sub_i32 s51, s12, s51
	s_mul_i32 s54, s50, 88
	s_add_i32 s54, s54, s51
	s_add_i32 s55, s54, 44
	s_waitcnt lgkmcnt(0)
	s_mul_i32 s50, s54, 1490
	s_lshr_b32 s50, s50, 16
	s_mul_i32 s51, s50, 44
	s_sub_i32 s51, s54, s51
	s_mul_i32 s51, s51, 0x100000
	s_lshl_b32 s52, s50, 6
	s_lshl_b32 s52, s52, 2
	s_add_u32 s51, s51, s52
	s_add_u32 s16, s8, s51
	s_addc_u32 s17, s9, 0
	s_add_u32 s18, s16, 0x40000
	s_addc_u32 s19, s17, 0
	s_add_u32 s20, s18, 0x40000
	s_addc_u32 s21, s19, 0
	s_add_u32 s22, s20, 0x40000
	s_addc_u32 s23, s21, 0
	global_load_dwordx4 v[32:35], v100, s[16:17] nt
	global_load_dwordx4 v[36:39], v100, s[18:19] nt
	global_load_dwordx4 v[40:43], v100, s[20:21] nt
	global_load_dwordx4 v[44:47], v100, s[22:23] nt
	s_mul_i32 s50, s55, 1490
	s_lshr_b32 s50, s50, 16
	s_mul_i32 s51, s50, 44
	s_sub_i32 s51, s55, s51
	s_mul_i32 s51, s51, 0x100000
	s_lshl_b32 s52, s50, 6
	s_lshl_b32 s52, s52, 2
	s_add_u32 s51, s51, s52
	s_add_u32 s24, s8, s51
	s_addc_u32 s25, s9, 0
	s_add_u32 s26, s24, 0x40000
	s_addc_u32 s27, s25, 0
	s_add_u32 s28, s26, 0x40000
	s_addc_u32 s29, s27, 0
	s_add_u32 s30, s28, 0x40000
	s_addc_u32 s31, s29, 0
	global_load_dwordx4 v[48:51], v100, s[24:25] nt
	global_load_dwordx4 v[52:55], v100, s[26:27] nt
	global_load_dwordx4 v[56:59], v100, s[28:29] nt
	global_load_dwordx4 v[60:63], v100, s[30:31] nt
	s_mov_b32 s14, 1
	s_mov_b32 s15, 0

; __device__ __forceinline__ void tjob_load(const TJob& j, int tile, f32x4 (&v)[4]) {
;     const int tid = threadIdx.x, nkt = j.K >> 7, tn = tile / nkt, tk = tile - tn * nkt;
;     const int n = tn * 64 + (tid & 15) * 4, kr = tid >> 4, col = map_col(j.map, n);
; #pragma unroll
;     for (int i = 0; i < 4; ++i) v[i] = col >= 0 ? __builtin_nontemporal_load((const f32x4*)(j.src + (size_t)(tk * 128 + kr + 32 * i) * j.ld_src + col)) : (f32x4){0.f, 0.f, 0.f, 0.f};
; __device__ __forceinline__ void transpose_jobs(const TJob* jobs, int njobs, int bi, int nblk, LAS unsigned char* lds) {
;     ...
;     while (t < total) {
;         const int tn = t + nblk; int nj = curj, nb = base; f32x4 w[4];
;         if (tn < total) { locate(tn, nj, nb); tjob_load(jobs[nj], tn - nb, w); }
;         tjob_store(jobs[curj], t - base, v, s);
;         if (tn < total) {
; #pragma unroll
;             for (int i = 0; i < 4; ++i) v[i] = w[i]; }
;         t = tn; curj = nj; base = nb;
.Ltr7_wd:
	v_mov_b32_e32 v0, v32
	v_mov_b32_e32 v1, v33
	v_mov_b32_e32 v2, v34
	v_mov_b32_e32 v3, v35
	v_mov_b32_e32 v4, v36
	v_mov_b32_e32 v5, v37
	v_mov_b32_e32 v6, v38
	v_mov_b32_e32 v7, v39
	v_mov_b32_e32 v8, v40
	v_mov_b32_e32 v9, v41
	v_mov_b32_e32 v10, v42
	v_mov_b32_e32 v11, v43
	v_mov_b32_e32 v12, v44
	v_mov_b32_e32 v13, v45
	v_mov_b32_e32 v14, v46
	v_mov_b32_e32 v15, v47
	v_mov_b32_e32 v16, v48
	v_mov_b32_e32 v17, v49
	v_mov_b32_e32 v18, v50
	v_mov_b32_e32 v19, v51
	v_mov_b32_e32 v20, v52
	v_mov_b32_e32 v21, v53
	v_mov_b32_e32 v22, v54
	v_mov_b32_e32 v23, v55
	v_mov_b32_e32 v24, v56
	v_mov_b32_e32 v25, v57
	v_mov_b32_e32 v26, v58
	v_mov_b32_e32 v27, v59
	v_mov_b32_e32 v28, v60
	v_mov_b32_e32 v29, v61
	v_mov_b32_e32 v30, v62
	v_mov_b32_e32 v31, v63
	s_mov_b32 s40, s54
	s_mov_b32 s43, s55
	s_mov_b32 s41, 1
	s_add_i32 s12, s12, 120
	s_mov_b32 s42, 0
	s_cmp_lt_u32 s12, 704
	s_cbranch_scc0 .Ltr7_nold
	s_mov_b32 s42, 1
	s_mul_i32 s50, s12, 1490
	s_lshr_b32 s50, s50, 16
	s_mul_i32 s51, s50, 44
	s_sub_i32 s51, s12, s51
	s_mul_i32 s54, s50, 88
	s_add_i32 s54, s54, s51
	s_add_i32 s55, s54, 44
	s_mul_i32 s50, s54, 1490
	s_lshr_b32 s50, s50, 16
	s_mul_i32 s51, s50, 44
	s_sub_i32 s51, s54, s51
	s_mul_i32 s51, s51, 0x100000
	s_lshl_b32 s52, s50, 6
	s_lshl_b32 s52, s52, 2
	s_add_u32 s51, s51, s52
	s_add_u32 s16, s8, s51
	s_addc_u32 s17, s9, 0
	s_add_u32 s18, s16, 0x40000
	s_addc_u32 s19, s17, 0
	s_add_u32 s20, s18, 0x40000
	s_addc_u32 s21, s19, 0
	s_add_u32 s22, s20, 0x40000
	s_addc_u32 s23, s21, 0
	global_load_dwordx4 v[32:35], v100, s[16:17] nt
	global_load_dwordx4 v[36:39], v100, s[18:19] nt
	global_load_dwordx4 v[40:43], v100, s[20:21] nt
	global_load_dwordx4 v[44:47], v100, s[22:23] nt
	s_mul_i32 s50, s55, 1490
	s_lshr_b32 s50, s50, 16
	s_mul_i32 s51, s50, 44
	s_sub_i32 s51, s55, s51
	s_mul_i32 s51, s51, 0x100000
	s_lshl_b32 s52, s50, 6
	s_lshl_b32 s52, s52, 2
	s_add_u32 s51, s51, s52
	s_add_u32 s24, s8, s51
	s_addc_u32 s25, s9, 0
	s_add_u32 s26, s24, 0x40000
	s_addc_u32 s27, s25, 0
	s_add_u32 s28, s26, 0x40000
	s_addc_u32 s29, s27, 0
	s_add_u32 s30, s28, 0x40000
	s_addc_u32 s31, s29, 0
	global_load_dwordx4 v[48:51], v100, s[24:25] nt
	global_load_dwordx4 v[52:55], v100, s[26:27] nt
	global_load_dwordx4 v[56:59], v100, s[28:29] nt
	global_load_dwordx4 v[60:63], v100, s[30:31] nt

; __device__ __forceinline__ void tjob_load(const TJob& j, int tile, f32x4 (&v)[4]) {
;     const int tid = threadIdx.x, nkt = j.K >> 7, tn = tile / nkt, tk = tile - tn * nkt;
;     const int n = tn * 64 + (tid & 15) * 4, kr = tid >> 4, col = map_col(j.map, n);
; #pragma unroll
;     for (int i = 0; i < 4; ++i) v[i] = col >= 0 ? __builtin_nontemporal_load((const f32x4*)(j.src + (size_t)(tk * 128 + kr + 32 * i) * j.ld_src + col)) : (f32x4){0.f, 0.f, 0.f, 0.f};
; __device__ __forceinline__ void transpose_jobs(const TJob* jobs, int njobs, int bi, int nblk, LAS unsigned char* lds) {
;     ...
;     f32x4 v[4]; int curj = 0, base = 0;
;     int t = bi;
;     auto locate = [&](int tt, int& jj, int& bb) { while (tt >= bb + (jobs[jj].Nout >> 6) * (jobs[jj].K >> 7)) { bb += (jobs[jj].Nout >> 6) * (jobs[jj].K >> 7); ++jj; } };
;     if (t < total) { locate(t, curj, base); tjob_load(jobs[curj], t - base, v); }
.Ltr8_go:
	s_waitcnt vmcnt(0)
	s_load_dwordx4 s[8:11], s[0:1], 0x128
	v_and_b32_e32 v105, 15, v160
	v_lshrrev_b32_e32 v106, 4, v160
	v_lshrrev_b32_e32 v107, 3, v160
	v_and_b32_e32 v108, 7, v160
	v_mul_u32_u24_e32 v100, 0xb000, v106
	v_lshl_add_u32 v100, v105, 4, v100
	v_mul_u32_u24_e32 v102, 2064, v105
	v_lshl_add_u32 v102, v106, 2, v102
	v_mul_u32_u24_e32 v103, 516, v107
	v_lshl_add_u32 v103, v108, 6, v103
	v_add_u32_e32 v104, 0x8400, v103
	v_mul_u32_u24_e32 v101, 0x1000, v107
	v_lshl_add_u32 v101, v108, 5, v101
	s_sub_i32 s12, s2, 64
	s_lshr_b32 s54, s12, 4
	s_lshl_b32 s54, s54, 5
	s_and_b32 s50, s12, 15
	s_add_i32 s54, s54, s50
	s_add_i32 s55, s54, 16
	s_waitcnt lgkmcnt(0)
	s_lshr_b32 s50, s54, 4
	s_and_b32 s51, s54, 15
	s_mul_i32 s51, s51, 0x580000
	s_lshr_b32 s52, s50, 2
	s_lshl_b32 s52, s52, 7
	s_and_b32 s53, s50, 1
	s_lshl_b32 s53, s53, 6
	s_add_i32 s52, s52, s53
	s_bfe_u32 s53, s50, 0x10001
	s_mul_i32 s53, s53, 5632
	s_add_i32 s52, s52, s53
	s_lshl_b32 s52, s52, 2
	s_add_u32 s51, s51, s52
	s_add_u32 s16, s8, s51
	s_addc_u32 s17, s9, 0
	s_add_u32 s18, s16, 0x160000
	s_addc_u32 s19, s17, 0
	s_add_u32 s20, s18, 0x160000
	s_addc_u32 s21, s19, 0
	s_add_u32 s22, s20, 0x160000
	s_addc_u32 s23, s21, 0
	global_load_dwordx4 v[32:35], v100, s[16:17] nt
	global_load_dwordx4 v[36:39], v100, s[18:19] nt
	global_load_dwordx4 v[40:43], v100, s[20:21] nt
	global_load_dwordx4 v[44:47], v100, s[22:23] nt
	s_lshr_b32 s50, s55, 4
	s_and_b32 s51, s55, 15
	s_mul_i32 s51, s51, 0x580000
	s_lshr_b32 s52, s50, 2
	s_lshl_b32 s52, s52, 7
	s_and_b32 s53, s50, 1
	s_lshl_b32 s53, s53, 6
	s_add_i32 s52, s52, s53
	s_bfe_u32 s53, s50, 0x10001
	s_mul_i32 s53, s53, 5632
	s_add_i32 s52, s52, s53
	s_lshl_b32 s52, s52, 2
	s_add_u32 s51, s51, s52
	s_add_u32 s24, s8, s51
	s_addc_u32 s25, s9, 0
	s_add_u32 s26, s24, 0x160000
	s_addc_u32 s27, s25, 0
	s_add_u32 s28, s26, 0x160000
	s_addc_u32 s29, s27, 0
	s_add_u32 s30, s28, 0x160000
	s_addc_u32 s31, s29, 0
	global_load_dwordx4 v[48:51], v100, s[24:25] nt
	global_load_dwordx4 v[52:55], v100, s[26:27] nt
	global_load_dwordx4 v[56:59], v100, s[28:29] nt
	global_load_dwordx4 v[60:63], v100, s[30:31] nt
	s_mov_b32 s14, 1
	s_mov_b32 s15, 0

; __device__ __forceinline__ void tjob_load(const TJob& j, int tile, f32x4 (&v)[4]) {
;     const int tid = threadIdx.x, nkt = j.K >> 7, tn = tile / nkt, tk = tile - tn * nkt;
;     const int n = tn * 64 + (tid & 15) * 4, kr = tid >> 4, col = map_col(j.map, n);
; #pragma unroll
;     for (int i = 0; i < 4; ++i) v[i] = col >= 0 ? __builtin_nontemporal_load((const f32x4*)(j.src + (size_t)(tk * 128 + kr + 32 * i) * j.ld_src + col)) : (f32x4){0.f, 0.f, 0.f, 0.f};
; __device__ __forceinline__ void transpose_jobs(const TJob* jobs, int njobs, int bi, int nblk, LAS unsigned char* lds) {
;     ...
;     while (t < total) {
;         const int tn = t + nblk; int nj = curj, nb = base; f32x4 w[4];
;         if (tn < total) { locate(tn, nj, nb); tjob_load(jobs[nj], tn - nb, w); }
;         tjob_store(jobs[curj], t - base, v, s);
;         if (tn < total) {
; #pragma unroll
;             for (int i = 0; i < 4; ++i) v[i] = w[i]; }
;         t = tn; curj = nj; base = nb;
.Ltr8_wd:
	v_mov_b32_e32 v0, v32
	v_mov_b32_e32 v1, v33
	v_mov_b32_e32 v2, v34
	v_mov_b32_e32 v3, v35
	v_mov_b32_e32 v4, v36
	v_mov_b32_e32 v5, v37
	v_mov_b32_e32 v6, v38
	v_mov_b32_e32 v7, v39
	v_mov_b32_e32 v8, v40
	v_mov_b32_e32 v9, v41
	v_mov_b32_e32 v10, v42
	v_mov_b32_e32 v11, v43
	v_mov_b32_e32 v12, v44
	v_mov_b32_e32 v13, v45
	v_mov_b32_e32 v14, v46
	v_mov_b32_e32 v15, v47
	v_mov_b32_e32 v16, v48
	v_mov_b32_e32 v17, v49
	v_mov_b32_e32 v18, v50
	v_mov_b32_e32 v19, v51
	v_mov_b32_e32 v20, v52
	v_mov_b32_e32 v21, v53
	v_mov_b32_e32 v22, v54
	v_mov_b32_e32 v23, v55
	v_mov_b32_e32 v24, v56
	v_mov_b32_e32 v25, v57
	v_mov_b32_e32 v26, v58
	v_mov_b32_e32 v27, v59
	v_mov_b32_e32 v28, v60
	v_mov_b32_e32 v29, v61
	v_mov_b32_e32 v30, v62
	v_mov_b32_e32 v31, v63
	s_mov_b32 s40, s54
	s_mov_b32 s43, s55
	s_mov_b32 s41, 1
	s_add_i32 s12, s12, 192
	s_mov_b32 s42, 0
	s_cmp_lt_u32 s12, 1408
	s_cbranch_scc0 .Ltr8_nold
	s_mov_b32 s42, 1
	s_lshr_b32 s54, s12, 4
	s_lshl_b32 s54, s54, 5
	s_and_b32 s50, s12, 15
	s_add_i32 s54, s54, s50
	s_add_i32 s55, s54, 16
	s_lshr_b32 s50, s54, 4
	s_and_b32 s51, s54, 15
	s_mul_i32 s51, s51, 0x580000
	s_lshr_b32 s52, s50, 2
	s_lshl_b32 s52, s52, 7
	s_and_b32 s53, s50, 1
	s_lshl_b32 s53, s53, 6
	s_add_i32 s52, s52, s53
	s_bfe_u32 s53, s50, 0x10001
	s_mul_i32 s53, s53, 5632
	s_add_i32 s52, s52, s53
	s_lshl_b32 s52, s52, 2
	s_add_u32 s51, s51, s52
	s_add_u32 s16, s8, s51
	s_addc_u32 s17, s9, 0
	s_add_u32 s18, s16, 0x160000
	s_addc_u32 s19, s17, 0
	s_add_u32 s20, s18, 0x160000
	s_addc_u32 s21, s19, 0
	s_add_u32 s22, s20, 0x160000
	s_addc_u32 s23, s21, 0
	global_load_dwordx4 v[32:35], v100, s[16:17] nt
	global_load_dwordx4 v[36:39], v100, s[18:19] nt
	global_load_dwordx4 v[40:43], v100, s[20:21] nt
	global_load_dwordx4 v[44:47], v100, s[22:23] nt
	s_lshr_b32 s50, s55, 4
	s_and_b32 s51, s55, 15
	s_mul_i32 s51, s51, 0x580000
	s_lshr_b32 s52, s50, 2
	s_lshl_b32 s52, s52, 7
	s_and_b32 s53, s50, 1
	s_lshl_b32 s53, s53, 6
	s_add_i32 s52, s52, s53
	s_bfe_u32 s53, s50, 0x10001
	s_mul_i32 s53, s53, 5632
	s_add_i32 s52, s52, s53
	s_lshl_b32 s52, s52, 2
	s_add_u32 s51, s51, s52
	s_add_u32 s24, s8, s51
	s_addc_u32 s25, s9, 0
	s_add_u32 s26, s24, 0x160000
	s_addc_u32 s27, s25, 0
	s_add_u32 s28, s26, 0x160000
	s_addc_u32 s29, s27, 0
	s_add_u32 s30, s28, 0x160000
	s_addc_u32 s31, s29, 0
	global_load_dwordx4 v[48:51], v100, s[24:25] nt
	global_load_dwordx4 v[52:55], v100, s[26:27] nt
	global_load_dwordx4 v[56:59], v100, s[28:29] nt
	global_load_dwordx4 v[60:63], v100, s[30:31] nt
